# A/B of the priority flips: the s_setprio 0 / s_setprio 1 pair in the middle of each 32-MFMA block of the chain K-loops removed (one raise per block)
# baseline (speedup 1.0000x reference)
.LBB0_391:
	ds_read_b128 v[148:151], v144
	ds_read_b128 v[152:155], v144 offset:1024
	ds_read_b128 v[156:159], v144 offset:2048
	ds_read_b128 v[160:163], v144 offset:3072
	ds_read_b128 v[174:177], v145
	ds_read_b128 v[178:181], v145 offset:1024
	ds_read_b128 v[182:185], v145 offset:2048
	ds_read_b128 v[186:189], v145 offset:3072
	v_lshl_add_u64 v[236:237], v[142:143], 0, s[62:63]
	s_mov_b32 m0, s55
	v_lshl_add_u64 v[238:239], v[236:237], 0, s[44:45]
	ds_read_b128 v[190:193], v195
	ds_read_b128 v[208:211], v195 offset:1024
	ds_read_b128 v[212:215], v195 offset:2048
	ds_read_b128 v[216:219], v195 offset:3072
	ds_read_b128 v[220:223], v195 offset:4096
	ds_read_b128 v[224:227], v195 offset:5120
	ds_read_b128 v[228:231], v195 offset:6144
	ds_read_b128 v[232:235], v195 offset:7168
	global_load_lds_dwordx4 v[238:239], off
	v_lshl_add_u64 v[238:239], v[140:141], 0, s[62:63]
	v_lshl_add_u64 v[240:241], v[238:239], 0, s[44:45]
	s_mov_b32 m0, s97
	s_nop 0
	global_load_lds_dwordx4 v[240:241], off
	s_waitcnt vmcnt(8)
	s_waitcnt lgkmcnt(0)
	s_barrier
	s_setprio 1
	s_waitcnt lgkmcnt(0)
	v_mfma_f32_16x16x32_bf16 v[124:127], v[148:151], v[190:193], v[124:127]
	v_mfma_f32_16x16x32_bf16 v[120:123], v[156:159], v[190:193], v[120:123]
	v_mfma_f32_16x16x32_bf16 v[116:119], v[148:151], v[212:215], v[116:119]
	v_mfma_f32_16x16x32_bf16 v[112:115], v[156:159], v[212:215], v[112:115]
	v_mfma_f32_16x16x32_bf16 v[108:111], v[148:151], v[220:223], v[108:111]
	v_mfma_f32_16x16x32_bf16 v[104:107], v[156:159], v[220:223], v[104:107]
	v_mfma_f32_16x16x32_bf16 v[100:103], v[148:151], v[228:231], v[100:103]
	v_mfma_f32_16x16x32_bf16 v[96:99], v[156:159], v[228:231], v[96:99]
	v_mfma_f32_16x16x32_bf16 v[124:127], v[152:155], v[208:211], v[124:127]
	v_mfma_f32_16x16x32_bf16 v[120:123], v[160:163], v[208:211], v[120:123]
	v_mfma_f32_16x16x32_bf16 v[116:119], v[152:155], v[216:219], v[116:119]
	v_mfma_f32_16x16x32_bf16 v[112:115], v[160:163], v[216:219], v[112:115]
	v_mfma_f32_16x16x32_bf16 v[108:111], v[152:155], v[224:227], v[108:111]
	v_mfma_f32_16x16x32_bf16 v[104:107], v[160:163], v[224:227], v[104:107]
	v_mfma_f32_16x16x32_bf16 v[100:103], v[152:155], v[232:235], v[100:103]
	v_mfma_f32_16x16x32_bf16 v[96:99], v[160:163], v[232:235], v[96:99]
	v_mfma_f32_16x16x32_bf16 v[92:95], v[174:177], v[190:193], v[92:95]
	v_mfma_f32_16x16x32_bf16 v[88:91], v[182:185], v[190:193], v[88:91]
	v_mfma_f32_16x16x32_bf16 v[84:87], v[174:177], v[212:215], v[84:87]
	v_mfma_f32_16x16x32_bf16 v[80:83], v[182:185], v[212:215], v[80:83]
	v_mfma_f32_16x16x32_bf16 v[76:79], v[174:177], v[220:223], v[76:79]
	v_mfma_f32_16x16x32_bf16 v[72:75], v[182:185], v[220:223], v[72:75]
	v_mfma_f32_16x16x32_bf16 v[68:71], v[174:177], v[228:231], v[68:71]
	v_mfma_f32_16x16x32_bf16 v[64:67], v[182:185], v[228:231], v[64:67]
	v_mfma_f32_16x16x32_bf16 v[92:95], v[178:181], v[208:211], v[92:95]
	v_mfma_f32_16x16x32_bf16 v[88:91], v[186:189], v[208:211], v[88:91]
	v_mfma_f32_16x16x32_bf16 v[84:87], v[178:181], v[216:219], v[84:87]
	v_mfma_f32_16x16x32_bf16 v[80:83], v[186:189], v[216:219], v[80:83]
	v_mfma_f32_16x16x32_bf16 v[76:79], v[178:181], v[224:227], v[76:79]
	v_mfma_f32_16x16x32_bf16 v[72:75], v[186:189], v[224:227], v[72:75]
	v_mfma_f32_16x16x32_bf16 v[68:71], v[178:181], v[232:235], v[68:71]
	v_mfma_f32_16x16x32_bf16 v[64:67], v[186:189], v[232:235], v[64:67]
	s_setprio 0
	s_barrier
	v_lshl_add_u64 v[240:241], v[128:129], 0, s[62:63]
	s_mov_b32 m0, s2
	v_lshl_add_u64 v[242:243], v[240:241], 0, s[46:47]
	ds_read_b128 v[190:193], v195 offset:16384
	ds_read_b128 v[208:211], v195 offset:17408
	ds_read_b128 v[212:215], v195 offset:18432
	ds_read_b128 v[216:219], v195 offset:19456
	ds_read_b128 v[220:223], v195 offset:20480
	ds_read_b128 v[224:227], v195 offset:21504
	ds_read_b128 v[228:231], v195 offset:22528
	ds_read_b128 v[232:235], v195 offset:23552
	global_load_lds_dwordx4 v[242:243], off
	v_lshl_add_u64 v[242:243], v[130:131], 0, s[62:63]
	v_lshl_add_u64 v[244:245], v[242:243], 0, s[46:47]
	s_mov_b32 m0, s16
	s_nop 0
	global_load_lds_dwordx4 v[244:245], off
	v_lshl_add_u64 v[244:245], v[138:139], 0, s[62:63]
	v_lshl_add_u64 v[246:247], v[244:245], 0, s[46:47]
	s_mov_b32 m0, s17
	s_nop 0
	global_load_lds_dwordx4 v[246:247], off
	v_lshl_add_u64 v[246:247], v[136:137], 0, s[62:63]
	v_lshl_add_u64 v[248:249], v[246:247], 0, s[46:47]
	s_mov_b32 m0, s14
	s_nop 0
	global_load_lds_dwordx4 v[248:249], off
	v_lshl_add_u64 v[248:249], v[132:133], 0, s[62:63]
	v_lshl_add_u64 v[250:251], v[248:249], 0, s[46:47]
	s_mov_b32 m0, s89
	s_nop 0
	global_load_lds_dwordx4 v[250:251], off
	v_lshl_add_u64 v[250:251], v[134:135], 0, s[62:63]
	v_lshl_add_u64 v[166:167], v[250:251], 0, s[46:47]
	s_mov_b32 m0, s90
	s_nop 0
	global_load_lds_dwordx4 v[166:167], off
	s_waitcnt vmcnt(8)
	s_waitcnt lgkmcnt(0)
	s_barrier
	s_setprio 1
	s_waitcnt lgkmcnt(0)
	v_mfma_f32_16x16x32_bf16 v[60:63], v[148:151], v[190:193], v[60:63]
	v_mfma_f32_16x16x32_bf16 v[56:59], v[156:159], v[190:193], v[56:59]
	v_mfma_f32_16x16x32_bf16 v[52:55], v[148:151], v[212:215], v[52:55]
	v_mfma_f32_16x16x32_bf16 v[48:51], v[156:159], v[212:215], v[48:51]
	v_mfma_f32_16x16x32_bf16 v[44:47], v[148:151], v[220:223], v[44:47]
	v_mfma_f32_16x16x32_bf16 v[40:43], v[156:159], v[220:223], v[40:43]
	v_mfma_f32_16x16x32_bf16 v[36:39], v[148:151], v[228:231], v[36:39]
	v_mfma_f32_16x16x32_bf16 v[32:35], v[156:159], v[228:231], v[32:35]
	v_mfma_f32_16x16x32_bf16 v[60:63], v[152:155], v[208:211], v[60:63]
	v_mfma_f32_16x16x32_bf16 v[56:59], v[160:163], v[208:211], v[56:59]
	v_mfma_f32_16x16x32_bf16 v[52:55], v[152:155], v[216:219], v[52:55]
	v_mfma_f32_16x16x32_bf16 v[48:51], v[160:163], v[216:219], v[48:51]
	v_mfma_f32_16x16x32_bf16 v[44:47], v[152:155], v[224:227], v[44:47]
	v_mfma_f32_16x16x32_bf16 v[40:43], v[160:163], v[224:227], v[40:43]
	v_mfma_f32_16x16x32_bf16 v[36:39], v[152:155], v[232:235], v[36:39]
	v_mfma_f32_16x16x32_bf16 v[32:35], v[160:163], v[232:235], v[32:35]
	v_mfma_f32_16x16x32_bf16 v[28:31], v[174:177], v[190:193], v[28:31]
	v_mfma_f32_16x16x32_bf16 v[24:27], v[182:185], v[190:193], v[24:27]
	v_mfma_f32_16x16x32_bf16 v[20:23], v[174:177], v[212:215], v[20:23]
	v_mfma_f32_16x16x32_bf16 v[16:19], v[182:185], v[212:215], v[16:19]
	v_mfma_f32_16x16x32_bf16 v[12:15], v[174:177], v[220:223], v[12:15]
	v_mfma_f32_16x16x32_bf16 v[8:11], v[182:185], v[220:223], v[8:11]
	v_mfma_f32_16x16x32_bf16 v[4:7], v[174:177], v[228:231], v[4:7]
	v_mfma_f32_16x16x32_bf16 v[0:3], v[182:185], v[228:231], v[0:3]
	v_mfma_f32_16x16x32_bf16 v[28:31], v[178:181], v[208:211], v[28:31]
	v_mfma_f32_16x16x32_bf16 v[24:27], v[186:189], v[208:211], v[24:27]
	v_mfma_f32_16x16x32_bf16 v[20:23], v[178:181], v[216:219], v[20:23]
	v_mfma_f32_16x16x32_bf16 v[16:19], v[186:189], v[216:219], v[16:19]
	v_mfma_f32_16x16x32_bf16 v[12:15], v[178:181], v[224:227], v[12:15]
	v_mfma_f32_16x16x32_bf16 v[8:11], v[186:189], v[224:227], v[8:11]
	v_mfma_f32_16x16x32_bf16 v[4:7], v[178:181], v[232:235], v[4:7]
	v_mfma_f32_16x16x32_bf16 v[0:3], v[186:189], v[232:235], v[0:3]
	s_setprio 0
	s_barrier
	ds_read_b128 v[148:151], v146
	ds_read_b128 v[152:155], v146 offset:1024
	ds_read_b128 v[156:159], v146 offset:2048
	ds_read_b128 v[160:163], v146 offset:3072
	ds_read_b128 v[174:177], v147
	ds_read_b128 v[178:181], v147 offset:1024
	ds_read_b128 v[182:185], v147 offset:2048
	ds_read_b128 v[186:189], v147 offset:3072
	s_mov_b32 m0, s91
	v_lshl_add_u64 v[166:167], v[236:237], 0, s[46:47]
	ds_read_b128 v[190:193], v195 offset:32768
	ds_read_b128 v[208:211], v195 offset:33792
	ds_read_b128 v[212:215], v195 offset:34816
	ds_read_b128 v[216:219], v195 offset:35840
	ds_read_b128 v[220:223], v195 offset:36864
	ds_read_b128 v[224:227], v195 offset:37888
	ds_read_b128 v[228:231], v195 offset:38912
	ds_read_b128 v[232:235], v195 offset:39936
	global_load_lds_dwordx4 v[166:167], off
	v_lshl_add_u64 v[166:167], v[238:239], 0, s[46:47]
	s_mov_b32 m0, s92
	s_nop 0
	global_load_lds_dwordx4 v[166:167], off
	s_waitcnt vmcnt(8)
	s_waitcnt lgkmcnt(0)
	s_barrier
	s_setprio 1
	s_waitcnt lgkmcnt(0)
	v_mfma_f32_16x16x32_bf16 v[124:127], v[148:151], v[190:193], v[124:127]
	v_mfma_f32_16x16x32_bf16 v[120:123], v[156:159], v[190:193], v[120:123]
	v_mfma_f32_16x16x32_bf16 v[116:119], v[148:151], v[212:215], v[116:119]
	v_mfma_f32_16x16x32_bf16 v[112:115], v[156:159], v[212:215], v[112:115]
	v_mfma_f32_16x16x32_bf16 v[108:111], v[148:151], v[220:223], v[108:111]
	v_mfma_f32_16x16x32_bf16 v[104:107], v[156:159], v[220:223], v[104:107]
	v_mfma_f32_16x16x32_bf16 v[100:103], v[148:151], v[228:231], v[100:103]
	v_mfma_f32_16x16x32_bf16 v[96:99], v[156:159], v[228:231], v[96:99]
	v_mfma_f32_16x16x32_bf16 v[124:127], v[152:155], v[208:211], v[124:127]
	v_mfma_f32_16x16x32_bf16 v[120:123], v[160:163], v[208:211], v[120:123]
	v_mfma_f32_16x16x32_bf16 v[116:119], v[152:155], v[216:219], v[116:119]
	v_mfma_f32_16x16x32_bf16 v[112:115], v[160:163], v[216:219], v[112:115]
	v_mfma_f32_16x16x32_bf16 v[108:111], v[152:155], v[224:227], v[108:111]
	v_mfma_f32_16x16x32_bf16 v[104:107], v[160:163], v[224:227], v[104:107]
	v_mfma_f32_16x16x32_bf16 v[100:103], v[152:155], v[232:235], v[100:103]
	v_mfma_f32_16x16x32_bf16 v[96:99], v[160:163], v[232:235], v[96:99]
	v_mfma_f32_16x16x32_bf16 v[92:95], v[174:177], v[190:193], v[92:95]
	v_mfma_f32_16x16x32_bf16 v[88:91], v[182:185], v[190:193], v[88:91]
	v_mfma_f32_16x16x32_bf16 v[84:87], v[174:177], v[212:215], v[84:87]
	v_mfma_f32_16x16x32_bf16 v[80:83], v[182:185], v[212:215], v[80:83]
	v_mfma_f32_16x16x32_bf16 v[76:79], v[174:177], v[220:223], v[76:79]
	v_mfma_f32_16x16x32_bf16 v[72:75], v[182:185], v[220:223], v[72:75]
	v_mfma_f32_16x16x32_bf16 v[68:71], v[174:177], v[228:231], v[68:71]
	v_mfma_f32_16x16x32_bf16 v[64:67], v[182:185], v[228:231], v[64:67]
	v_mfma_f32_16x16x32_bf16 v[92:95], v[178:181], v[208:211], v[92:95]
	v_mfma_f32_16x16x32_bf16 v[88:91], v[186:189], v[208:211], v[88:91]
	v_mfma_f32_16x16x32_bf16 v[84:87], v[178:181], v[216:219], v[84:87]
	v_mfma_f32_16x16x32_bf16 v[80:83], v[186:189], v[216:219], v[80:83]
	v_mfma_f32_16x16x32_bf16 v[76:79], v[178:181], v[224:227], v[76:79]
	v_mfma_f32_16x16x32_bf16 v[72:75], v[186:189], v[224:227], v[72:75]
	v_mfma_f32_16x16x32_bf16 v[68:71], v[178:181], v[232:235], v[68:71]
	v_mfma_f32_16x16x32_bf16 v[64:67], v[186:189], v[232:235], v[64:67]
	s_setprio 0
	s_barrier
	s_mov_b32 m0, s15
	v_lshl_add_u64 v[166:167], v[240:241], 0, s[48:49]
	ds_read_b128 v[190:193], v195 offset:49152
	ds_read_b128 v[208:211], v195 offset:50176
	ds_read_b128 v[212:215], v195 offset:51200
	ds_read_b128 v[216:219], v195 offset:52224
	ds_read_b128 v[220:223], v195 offset:53248
	ds_read_b128 v[224:227], v195 offset:54272
	ds_read_b128 v[228:231], v195 offset:55296
	ds_read_b128 v[232:235], v195 offset:56320
	global_load_lds_dwordx4 v[166:167], off
	v_lshl_add_u64 v[166:167], v[242:243], 0, s[48:49]
	s_mov_b32 m0, s33
	s_nop 0
	global_load_lds_dwordx4 v[166:167], off
	v_lshl_add_u64 v[166:167], v[244:245], 0, s[48:49]
	s_mov_b32 m0, s3
	s_nop 0
	global_load_lds_dwordx4 v[166:167], off
	v_lshl_add_u64 v[166:167], v[246:247], 0, s[48:49]
	s_mov_b32 m0, s20
	s_nop 0
	global_load_lds_dwordx4 v[166:167], off
	v_lshl_add_u64 v[166:167], v[248:249], 0, s[48:49]
	s_mov_b32 m0, s93
	s_nop 0
	global_load_lds_dwordx4 v[166:167], off
	v_lshl_add_u64 v[166:167], v[250:251], 0, s[48:49]
	s_mov_b32 m0, s94
	s_nop 0
	global_load_lds_dwordx4 v[166:167], off
	s_waitcnt vmcnt(8)
	s_waitcnt lgkmcnt(0)
	s_barrier
	s_setprio 1
	s_waitcnt lgkmcnt(0)
	v_mfma_f32_16x16x32_bf16 v[60:63], v[148:151], v[190:193], v[60:63]
	v_mfma_f32_16x16x32_bf16 v[56:59], v[156:159], v[190:193], v[56:59]
	v_mfma_f32_16x16x32_bf16 v[52:55], v[148:151], v[212:215], v[52:55]
	v_mfma_f32_16x16x32_bf16 v[48:51], v[156:159], v[212:215], v[48:51]
	v_mfma_f32_16x16x32_bf16 v[44:47], v[148:151], v[220:223], v[44:47]
	v_mfma_f32_16x16x32_bf16 v[40:43], v[156:159], v[220:223], v[40:43]
	v_mfma_f32_16x16x32_bf16 v[36:39], v[148:151], v[228:231], v[36:39]
	v_mfma_f32_16x16x32_bf16 v[32:35], v[156:159], v[228:231], v[32:35]
	v_mfma_f32_16x16x32_bf16 v[60:63], v[152:155], v[208:211], v[60:63]
	v_mfma_f32_16x16x32_bf16 v[56:59], v[160:163], v[208:211], v[56:59]
	v_mfma_f32_16x16x32_bf16 v[52:55], v[152:155], v[216:219], v[52:55]
	v_mfma_f32_16x16x32_bf16 v[48:51], v[160:163], v[216:219], v[48:51]
	v_mfma_f32_16x16x32_bf16 v[44:47], v[152:155], v[224:227], v[44:47]
	v_mfma_f32_16x16x32_bf16 v[40:43], v[160:163], v[224:227], v[40:43]
	v_mfma_f32_16x16x32_bf16 v[36:39], v[152:155], v[232:235], v[36:39]
	v_mfma_f32_16x16x32_bf16 v[32:35], v[160:163], v[232:235], v[32:35]
	v_mfma_f32_16x16x32_bf16 v[28:31], v[174:177], v[190:193], v[28:31]
	v_mfma_f32_16x16x32_bf16 v[24:27], v[182:185], v[190:193], v[24:27]
	v_mfma_f32_16x16x32_bf16 v[20:23], v[174:177], v[212:215], v[20:23]
	s_add_u32 s62, s62, 0x100
	v_mfma_f32_16x16x32_bf16 v[16:19], v[182:185], v[212:215], v[16:19]
	s_addc_u32 s63, s63, 0
	v_mfma_f32_16x16x32_bf16 v[12:15], v[174:177], v[220:223], v[12:15]
	s_add_i32 s32, s22, 2
	v_mfma_f32_16x16x32_bf16 v[8:11], v[182:185], v[220:223], v[8:11]
	s_add_i32 s99, s22, -4
	v_mfma_f32_16x16x32_bf16 v[4:7], v[174:177], v[228:231], v[4:7]
	s_cmp_ge_i32 s99, s29
	v_mfma_f32_16x16x32_bf16 v[0:3], v[182:185], v[228:231], v[0:3]
	s_cselect_b32 s98, 0, 1
	v_mfma_f32_16x16x32_bf16 v[28:31], v[178:181], v[208:211], v[28:31]
	s_cmp_eq_u32 s34, s32
	v_mfma_f32_16x16x32_bf16 v[24:27], v[186:189], v[208:211], v[24:27]
	s_cselect_b64 vcc, -1, 0
	v_mfma_f32_16x16x32_bf16 v[20:23], v[178:181], v[216:219], v[20:23]
	s_and_b64 vcc, s[66:67], vcc
	v_mfma_f32_16x16x32_bf16 v[16:19], v[186:189], v[216:219], v[16:19]
	s_cselect_b32 s98, 0, s98
	v_mfma_f32_16x16x32_bf16 v[12:15], v[178:181], v[224:227], v[12:15]
	s_and_b64 vcc, exec, s[8:9]
	v_mfma_f32_16x16x32_bf16 v[8:11], v[186:189], v[224:227], v[8:11]
	s_cselect_b32 s98, s98, 0
	v_mfma_f32_16x16x32_bf16 v[4:7], v[178:181], v[232:235], v[4:7]
	s_cmp_lg_u32 s98, 0
	v_mfma_f32_16x16x32_bf16 v[0:3], v[186:189], v[232:235], v[0:3]
	s_setprio 0
	s_barrier
	s_cbranch_scc1 .Lk_fastb
	s_and_b64 vcc, exec, s[8:9]
	s_cbranch_vccnz .LBB0_394
	s_waitcnt vmcnt(16)
	v_mov_b32_e32 v148, s82
	v_mov_b32_e32 v149, s21
	ds_read_b32 v148, v148
	ds_read_b32 v149, v149 offset:60
	s_mov_b64 s[64:65], 0
	s_waitcnt lgkmcnt(0)
	v_readfirstlane_b32 s8, v148
	v_readfirstlane_b32 s9, v149
	s_mul_i32 s9, s9, s28
	s_cmp_lt_u32 s8, s9
	s_cbranch_scc1 .LBB0_394
	buffer_inv sc1
	s_mov_b64 s[64:65], -1

.LBB0_2163:
	ds_read_b128 v[150:153], v146
	ds_read_b128 v[154:157], v146 offset:1024
	ds_read_b128 v[158:161], v146 offset:2048
	ds_read_b128 v[162:165], v146 offset:3072
	ds_read_b128 v[166:169], v147
	ds_read_b128 v[180:183], v147 offset:1024
	ds_read_b128 v[184:187], v147 offset:2048
	ds_read_b128 v[188:191], v147 offset:3072
	v_lshl_add_u64 v[242:243], v[144:145], 0, s[38:39]
	s_mov_b32 m0, s95
	v_lshl_add_u64 v[244:245], v[242:243], 0, s[78:79]
	ds_read_b128 v[192:195], v200
	ds_read_b128 v[196:199], v200 offset:1024
	ds_read_b128 v[218:221], v200 offset:2048
	ds_read_b128 v[222:225], v200 offset:3072
	ds_read_b128 v[226:229], v200 offset:4096
	ds_read_b128 v[230:233], v200 offset:5120
	ds_read_b128 v[234:237], v200 offset:6144
	ds_read_b128 v[238:241], v200 offset:7168
	global_load_lds_dwordx4 v[244:245], off
	v_lshl_add_u64 v[244:245], v[142:143], 0, s[38:39]
	v_lshl_add_u64 v[246:247], v[244:245], 0, s[78:79]
	s_mov_b32 m0, s96
	s_nop 0
	global_load_lds_dwordx4 v[246:247], off
	s_waitcnt vmcnt(8)
	s_waitcnt lgkmcnt(0)
	s_barrier
	s_setprio 1
	s_waitcnt lgkmcnt(0)
	v_mfma_f32_16x16x32_bf16 v[126:129], v[150:153], v[192:195], v[126:129]
	v_mfma_f32_16x16x32_bf16 v[122:125], v[158:161], v[192:195], v[122:125]
	v_mfma_f32_16x16x32_bf16 v[118:121], v[150:153], v[218:221], v[118:121]
	v_mfma_f32_16x16x32_bf16 v[114:117], v[158:161], v[218:221], v[114:117]
	v_mfma_f32_16x16x32_bf16 v[110:113], v[150:153], v[226:229], v[110:113]
	v_mfma_f32_16x16x32_bf16 v[106:109], v[158:161], v[226:229], v[106:109]
	v_mfma_f32_16x16x32_bf16 v[102:105], v[150:153], v[234:237], v[102:105]
	v_mfma_f32_16x16x32_bf16 v[98:101], v[158:161], v[234:237], v[98:101]
	v_mfma_f32_16x16x32_bf16 v[126:129], v[154:157], v[196:199], v[126:129]
	v_mfma_f32_16x16x32_bf16 v[122:125], v[162:165], v[196:199], v[122:125]
	v_mfma_f32_16x16x32_bf16 v[118:121], v[154:157], v[222:225], v[118:121]
	v_mfma_f32_16x16x32_bf16 v[114:117], v[162:165], v[222:225], v[114:117]
	v_mfma_f32_16x16x32_bf16 v[110:113], v[154:157], v[230:233], v[110:113]
	v_mfma_f32_16x16x32_bf16 v[106:109], v[162:165], v[230:233], v[106:109]
	v_mfma_f32_16x16x32_bf16 v[102:105], v[154:157], v[238:241], v[102:105]
	v_mfma_f32_16x16x32_bf16 v[98:101], v[162:165], v[238:241], v[98:101]
	v_mfma_f32_16x16x32_bf16 v[94:97], v[166:169], v[192:195], v[94:97]
	v_mfma_f32_16x16x32_bf16 v[90:93], v[184:187], v[192:195], v[90:93]
	v_mfma_f32_16x16x32_bf16 v[86:89], v[166:169], v[218:221], v[86:89]
	v_mfma_f32_16x16x32_bf16 v[82:85], v[184:187], v[218:221], v[82:85]
	v_mfma_f32_16x16x32_bf16 v[78:81], v[166:169], v[226:229], v[78:81]
	v_mfma_f32_16x16x32_bf16 v[74:77], v[184:187], v[226:229], v[74:77]
	v_mfma_f32_16x16x32_bf16 v[70:73], v[166:169], v[234:237], v[70:73]
	v_mfma_f32_16x16x32_bf16 v[66:69], v[184:187], v[234:237], v[66:69]
	v_mfma_f32_16x16x32_bf16 v[94:97], v[180:183], v[196:199], v[94:97]
	v_mfma_f32_16x16x32_bf16 v[90:93], v[188:191], v[196:199], v[90:93]
	v_mfma_f32_16x16x32_bf16 v[86:89], v[180:183], v[222:225], v[86:89]
	v_mfma_f32_16x16x32_bf16 v[82:85], v[188:191], v[222:225], v[82:85]
	v_mfma_f32_16x16x32_bf16 v[78:81], v[180:183], v[230:233], v[78:81]
	v_mfma_f32_16x16x32_bf16 v[74:77], v[188:191], v[230:233], v[74:77]
	v_mfma_f32_16x16x32_bf16 v[70:73], v[180:183], v[238:241], v[70:73]
	v_mfma_f32_16x16x32_bf16 v[66:69], v[188:191], v[238:241], v[66:69]
	s_setprio 0
	s_barrier
	v_lshl_add_u64 v[246:247], v[130:131], 0, s[38:39]
	s_mov_b32 m0, s2
	v_lshl_add_u64 v[248:249], v[246:247], 0, s[76:77]
	ds_read_b128 v[192:195], v200 offset:16384
	ds_read_b128 v[196:199], v200 offset:17408
	ds_read_b128 v[218:221], v200 offset:18432
	ds_read_b128 v[222:225], v200 offset:19456
	ds_read_b128 v[226:229], v200 offset:20480
	ds_read_b128 v[230:233], v200 offset:21504
	ds_read_b128 v[234:237], v200 offset:22528
	ds_read_b128 v[238:241], v200 offset:23552
	global_load_lds_dwordx4 v[248:249], off
	v_lshl_add_u64 v[248:249], v[132:133], 0, s[38:39]
	v_lshl_add_u64 v[250:251], v[248:249], 0, s[76:77]
	s_mov_b32 m0, s56
	s_nop 0
	global_load_lds_dwordx4 v[250:251], off
	v_lshl_add_u64 v[250:251], v[140:141], 0, s[38:39]
	v_lshl_add_u64 v[206:207], v[250:251], 0, s[76:77]
	s_mov_b32 m0, s19
	s_nop 0
	global_load_lds_dwordx4 v[206:207], off
	v_lshl_add_u64 v[206:207], v[138:139], 0, s[38:39]
	v_lshl_add_u64 v[204:205], v[206:207], 0, s[76:77]
	s_mov_b32 m0, s63
	s_nop 0
	global_load_lds_dwordx4 v[204:205], off
	v_lshl_add_u64 v[204:205], v[134:135], 0, s[38:39]
	v_lshl_add_u64 v[170:171], v[204:205], 0, s[76:77]
	s_mov_b32 m0, s53
	s_nop 0
	global_load_lds_dwordx4 v[170:171], off
	v_lshl_add_u64 v[170:171], v[136:137], 0, s[38:39]
	v_lshl_add_u64 v[208:209], v[170:171], 0, s[76:77]
	s_mov_b32 m0, s92
	s_nop 0
	global_load_lds_dwordx4 v[208:209], off
	s_waitcnt vmcnt(8)
	s_waitcnt lgkmcnt(0)
	s_barrier
	s_setprio 1
	s_waitcnt lgkmcnt(0)
	v_mfma_f32_16x16x32_bf16 v[62:65], v[150:153], v[192:195], v[62:65]
	v_mfma_f32_16x16x32_bf16 v[58:61], v[158:161], v[192:195], v[58:61]
	v_mfma_f32_16x16x32_bf16 v[54:57], v[150:153], v[218:221], v[54:57]
	v_mfma_f32_16x16x32_bf16 v[50:53], v[158:161], v[218:221], v[50:53]
	v_mfma_f32_16x16x32_bf16 v[46:49], v[150:153], v[226:229], v[46:49]
	v_mfma_f32_16x16x32_bf16 v[42:45], v[158:161], v[226:229], v[42:45]
	v_mfma_f32_16x16x32_bf16 v[38:41], v[150:153], v[234:237], v[38:41]
	v_mfma_f32_16x16x32_bf16 v[34:37], v[158:161], v[234:237], v[34:37]
	v_mfma_f32_16x16x32_bf16 v[62:65], v[154:157], v[196:199], v[62:65]
	v_mfma_f32_16x16x32_bf16 v[58:61], v[162:165], v[196:199], v[58:61]
	v_mfma_f32_16x16x32_bf16 v[54:57], v[154:157], v[222:225], v[54:57]
	v_mfma_f32_16x16x32_bf16 v[50:53], v[162:165], v[222:225], v[50:53]
	v_mfma_f32_16x16x32_bf16 v[46:49], v[154:157], v[230:233], v[46:49]
	v_mfma_f32_16x16x32_bf16 v[42:45], v[162:165], v[230:233], v[42:45]
	v_mfma_f32_16x16x32_bf16 v[38:41], v[154:157], v[238:241], v[38:41]
	v_mfma_f32_16x16x32_bf16 v[34:37], v[162:165], v[238:241], v[34:37]
	v_mfma_f32_16x16x32_bf16 v[30:33], v[166:169], v[192:195], v[30:33]
	v_mfma_f32_16x16x32_bf16 v[26:29], v[184:187], v[192:195], v[26:29]
	v_mfma_f32_16x16x32_bf16 v[22:25], v[166:169], v[218:221], v[22:25]
	v_mfma_f32_16x16x32_bf16 v[18:21], v[184:187], v[218:221], v[18:21]
	v_mfma_f32_16x16x32_bf16 v[14:17], v[166:169], v[226:229], v[14:17]
	v_mfma_f32_16x16x32_bf16 v[10:13], v[184:187], v[226:229], v[10:13]
	v_mfma_f32_16x16x32_bf16 v[6:9], v[166:169], v[234:237], v[6:9]
	v_mfma_f32_16x16x32_bf16 v[2:5], v[184:187], v[234:237], v[2:5]
	v_mfma_f32_16x16x32_bf16 v[30:33], v[180:183], v[196:199], v[30:33]
	v_mfma_f32_16x16x32_bf16 v[26:29], v[188:191], v[196:199], v[26:29]
	v_mfma_f32_16x16x32_bf16 v[22:25], v[180:183], v[222:225], v[22:25]
	v_mfma_f32_16x16x32_bf16 v[18:21], v[188:191], v[222:225], v[18:21]
	v_mfma_f32_16x16x32_bf16 v[14:17], v[180:183], v[230:233], v[14:17]
	v_mfma_f32_16x16x32_bf16 v[10:13], v[188:191], v[230:233], v[10:13]
	v_mfma_f32_16x16x32_bf16 v[6:9], v[180:183], v[238:241], v[6:9]
	v_mfma_f32_16x16x32_bf16 v[2:5], v[188:191], v[238:241], v[2:5]
	s_setprio 0
	s_barrier
	ds_read_b128 v[150:153], v148
	ds_read_b128 v[154:157], v148 offset:1024
	ds_read_b128 v[158:161], v148 offset:2048
	ds_read_b128 v[162:165], v148 offset:3072
	ds_read_b128 v[166:169], v149
	ds_read_b128 v[180:183], v149 offset:1024
	ds_read_b128 v[184:187], v149 offset:2048
	ds_read_b128 v[188:191], v149 offset:3072
	s_mov_b32 m0, s93
	v_lshl_add_u64 v[208:209], v[242:243], 0, s[76:77]
	ds_read_b128 v[192:195], v200 offset:32768
	ds_read_b128 v[196:199], v200 offset:33792
	ds_read_b128 v[218:221], v200 offset:34816
	ds_read_b128 v[222:225], v200 offset:35840
	ds_read_b128 v[226:229], v200 offset:36864
	ds_read_b128 v[230:233], v200 offset:37888
	ds_read_b128 v[234:237], v200 offset:38912
	ds_read_b128 v[238:241], v200 offset:39936
	global_load_lds_dwordx4 v[208:209], off
	v_lshl_add_u64 v[208:209], v[244:245], 0, s[76:77]
	s_mov_b32 m0, s54
	s_nop 0
	global_load_lds_dwordx4 v[208:209], off
	s_waitcnt vmcnt(8)
	s_waitcnt lgkmcnt(0)
	s_barrier
	s_setprio 1
	s_waitcnt lgkmcnt(0)
	v_mfma_f32_16x16x32_bf16 v[126:129], v[150:153], v[192:195], v[126:129]
	v_mfma_f32_16x16x32_bf16 v[122:125], v[158:161], v[192:195], v[122:125]
	v_mfma_f32_16x16x32_bf16 v[118:121], v[150:153], v[218:221], v[118:121]
	v_mfma_f32_16x16x32_bf16 v[114:117], v[158:161], v[218:221], v[114:117]
	v_mfma_f32_16x16x32_bf16 v[110:113], v[150:153], v[226:229], v[110:113]
	v_mfma_f32_16x16x32_bf16 v[106:109], v[158:161], v[226:229], v[106:109]
	v_mfma_f32_16x16x32_bf16 v[102:105], v[150:153], v[234:237], v[102:105]
	v_mfma_f32_16x16x32_bf16 v[98:101], v[158:161], v[234:237], v[98:101]
	v_mfma_f32_16x16x32_bf16 v[126:129], v[154:157], v[196:199], v[126:129]
	v_mfma_f32_16x16x32_bf16 v[122:125], v[162:165], v[196:199], v[122:125]
	v_mfma_f32_16x16x32_bf16 v[118:121], v[154:157], v[222:225], v[118:121]
	v_mfma_f32_16x16x32_bf16 v[114:117], v[162:165], v[222:225], v[114:117]
	v_mfma_f32_16x16x32_bf16 v[110:113], v[154:157], v[230:233], v[110:113]
	v_mfma_f32_16x16x32_bf16 v[106:109], v[162:165], v[230:233], v[106:109]
	v_mfma_f32_16x16x32_bf16 v[102:105], v[154:157], v[238:241], v[102:105]
	v_mfma_f32_16x16x32_bf16 v[98:101], v[162:165], v[238:241], v[98:101]
	v_mfma_f32_16x16x32_bf16 v[94:97], v[166:169], v[192:195], v[94:97]
	v_mfma_f32_16x16x32_bf16 v[90:93], v[184:187], v[192:195], v[90:93]
	v_mfma_f32_16x16x32_bf16 v[86:89], v[166:169], v[218:221], v[86:89]
	v_mfma_f32_16x16x32_bf16 v[82:85], v[184:187], v[218:221], v[82:85]
	v_mfma_f32_16x16x32_bf16 v[78:81], v[166:169], v[226:229], v[78:81]
	v_mfma_f32_16x16x32_bf16 v[74:77], v[184:187], v[226:229], v[74:77]
	v_mfma_f32_16x16x32_bf16 v[70:73], v[166:169], v[234:237], v[70:73]
	v_mfma_f32_16x16x32_bf16 v[66:69], v[184:187], v[234:237], v[66:69]
	v_mfma_f32_16x16x32_bf16 v[94:97], v[180:183], v[196:199], v[94:97]
	v_mfma_f32_16x16x32_bf16 v[90:93], v[188:191], v[196:199], v[90:93]
	v_mfma_f32_16x16x32_bf16 v[86:89], v[180:183], v[222:225], v[86:89]
	v_mfma_f32_16x16x32_bf16 v[82:85], v[188:191], v[222:225], v[82:85]
	v_mfma_f32_16x16x32_bf16 v[78:81], v[180:183], v[230:233], v[78:81]
	v_mfma_f32_16x16x32_bf16 v[74:77], v[188:191], v[230:233], v[74:77]
	v_mfma_f32_16x16x32_bf16 v[70:73], v[180:183], v[238:241], v[70:73]
	v_mfma_f32_16x16x32_bf16 v[66:69], v[188:191], v[238:241], v[66:69]
	s_setprio 0
	s_barrier
	s_mov_b32 m0, s33
	v_lshl_add_u64 v[208:209], v[246:247], 0, s[80:81]
	ds_read_b128 v[192:195], v200 offset:49152
	ds_read_b128 v[196:199], v200 offset:50176
	ds_read_b128 v[218:221], v200 offset:51200
	ds_read_b128 v[222:225], v200 offset:52224
	ds_read_b128 v[226:229], v200 offset:53248
	ds_read_b128 v[230:233], v200 offset:54272
	ds_read_b128 v[234:237], v200 offset:55296
	ds_read_b128 v[238:241], v200 offset:56320
	global_load_lds_dwordx4 v[208:209], off
	v_lshl_add_u64 v[208:209], v[248:249], 0, s[80:81]
	s_mov_b32 m0, s3
	v_lshl_add_u64 v[206:207], v[206:207], 0, s[80:81]
	global_load_lds_dwordx4 v[208:209], off
	v_lshl_add_u64 v[208:209], v[250:251], 0, s[80:81]
	s_mov_b32 m0, s47
	v_lshl_add_u64 v[204:205], v[204:205], 0, s[80:81]
	global_load_lds_dwordx4 v[208:209], off
	s_mov_b32 m0, s4
	v_lshl_add_u64 v[170:171], v[170:171], 0, s[80:81]
	global_load_lds_dwordx4 v[206:207], off
	s_mov_b32 m0, s55
	s_nop 0
	global_load_lds_dwordx4 v[204:205], off
	s_mov_b32 m0, s64
	s_nop 0
	global_load_lds_dwordx4 v[170:171], off
	s_waitcnt vmcnt(8)
	s_waitcnt lgkmcnt(0)
	s_barrier
	s_setprio 1
	s_waitcnt lgkmcnt(0)
	v_mfma_f32_16x16x32_bf16 v[62:65], v[150:153], v[192:195], v[62:65]
	v_mfma_f32_16x16x32_bf16 v[58:61], v[158:161], v[192:195], v[58:61]
	v_mfma_f32_16x16x32_bf16 v[54:57], v[150:153], v[218:221], v[54:57]
	v_mfma_f32_16x16x32_bf16 v[50:53], v[158:161], v[218:221], v[50:53]
	v_mfma_f32_16x16x32_bf16 v[46:49], v[150:153], v[226:229], v[46:49]
	v_mfma_f32_16x16x32_bf16 v[42:45], v[158:161], v[226:229], v[42:45]
	v_mfma_f32_16x16x32_bf16 v[38:41], v[150:153], v[234:237], v[38:41]
	v_mfma_f32_16x16x32_bf16 v[34:37], v[158:161], v[234:237], v[34:37]
	v_mfma_f32_16x16x32_bf16 v[62:65], v[154:157], v[196:199], v[62:65]
	v_mfma_f32_16x16x32_bf16 v[58:61], v[162:165], v[196:199], v[58:61]
	v_mfma_f32_16x16x32_bf16 v[54:57], v[154:157], v[222:225], v[54:57]
	v_mfma_f32_16x16x32_bf16 v[50:53], v[162:165], v[222:225], v[50:53]
	v_mfma_f32_16x16x32_bf16 v[46:49], v[154:157], v[230:233], v[46:49]
	v_mfma_f32_16x16x32_bf16 v[42:45], v[162:165], v[230:233], v[42:45]
	v_mfma_f32_16x16x32_bf16 v[38:41], v[154:157], v[238:241], v[38:41]
	v_mfma_f32_16x16x32_bf16 v[34:37], v[162:165], v[238:241], v[34:37]
	v_mfma_f32_16x16x32_bf16 v[30:33], v[166:169], v[192:195], v[30:33]
	v_mfma_f32_16x16x32_bf16 v[26:29], v[184:187], v[192:195], v[26:29]
	v_mfma_f32_16x16x32_bf16 v[22:25], v[166:169], v[218:221], v[22:25]
	s_add_u32 s38, s38, 0x100
	v_mfma_f32_16x16x32_bf16 v[18:21], v[184:187], v[218:221], v[18:21]
	s_addc_u32 s39, s39, 0
	v_mfma_f32_16x16x32_bf16 v[14:17], v[166:169], v[226:229], v[14:17]
	s_add_i32 s32, s62, 2
	v_mfma_f32_16x16x32_bf16 v[10:13], v[184:187], v[226:229], v[10:13]
	s_add_i32 s99, s62, -4
	v_mfma_f32_16x16x32_bf16 v[6:9], v[166:169], v[234:237], v[6:9]
	s_cmp_ge_i32 s99, s51
	v_mfma_f32_16x16x32_bf16 v[2:5], v[184:187], v[234:237], v[2:5]
	s_cselect_b32 s98, 0, 1
	v_mfma_f32_16x16x32_bf16 v[30:33], v[180:183], v[196:199], v[30:33]
	s_cmp_eq_u32 s94, s32
	v_mfma_f32_16x16x32_bf16 v[26:29], v[188:191], v[196:199], v[26:29]
	s_cselect_b64 vcc, -1, 0
	v_mfma_f32_16x16x32_bf16 v[22:25], v[180:183], v[222:225], v[22:25]
	s_and_b64 vcc, s[16:17], vcc
	v_mfma_f32_16x16x32_bf16 v[18:21], v[188:191], v[222:225], v[18:21]
	s_cselect_b32 s98, 0, s98
	v_mfma_f32_16x16x32_bf16 v[14:17], v[180:183], v[230:233], v[14:17]
	s_and_b64 vcc, exec, s[10:11]
	v_mfma_f32_16x16x32_bf16 v[10:13], v[188:191], v[230:233], v[10:13]
	s_cselect_b32 s98, s98, 0
	v_mfma_f32_16x16x32_bf16 v[6:9], v[180:183], v[238:241], v[6:9]
	s_cmp_lg_u32 s98, 0
	v_mfma_f32_16x16x32_bf16 v[2:5], v[188:191], v[238:241], v[2:5]
	s_setprio 0
	s_barrier
	s_cbranch_scc1 .Lk_fasta
	s_and_b64 vcc, exec, s[10:11]
	s_cbranch_vccnz .LBB0_2166
	s_waitcnt vmcnt(16)
	v_mov_b32_e32 v150, s50
	v_mov_b32_e32 v151, s5
	ds_read_b32 v150, v150
	ds_read_b32 v151, v151 offset:60
	s_mov_b64 s[40:41], 0
	s_waitcnt lgkmcnt(0)
	v_readfirstlane_b32 s10, v150
	v_readfirstlane_b32 s11, v151
	s_mul_i32 s11, s11, s18
	s_cmp_lt_u32 s10, s11
	s_cbranch_scc1 .LBB0_2166
	buffer_inv sc1
	s_mov_b64 s[40:41], -1
